# sample-attention loop: two one-line-per-lane loads per iteration touch the K/V lines of the tile two ahead (L2 warm-up), wait leaves them outstanding
# speedup vs baseline: 1.0034x; 1.0034x over previous
; #define LAS __attribute__((address_space(3)))
; __device__ __forceinline__ void sattn_unit(const Args& a, LAS unsigned char* lds, const LAS float* bt, int db, int h, int t, int tid, int wave, int lane) {
;     asm volatile("" : "+v"(lane), "+v"(tid));
;     const int qg = wave & 1, dvh = (wave >> 1) & 1, ksp = wave >> 2, hi = lane >> 5, r32 = lane & 31;
;     const bf16* Qb = (const bf16*)(a.ws + WS_Q); const bf16* Kb = (const bf16*)(a.ws + WS_K); const bf16* Vb = (const bf16*)(a.ws + WS_V); bf16* Ob = (bf16*)(a.ws + WS_O);
;     const float* CK = a.in[I_CK]; const float* CV = a.in[I_CV];
;     const LAS float* bth = bt + h * 196;
;     bf16x8 qr[4];
;     { const bf16* qp = Qb + (size_t)(MP + db * 64 + qg * 32 + r32) * 1024 + h * 128 + t * 64 + hi * 8;
; #pragma unroll
;       for (int d0 = 0; d0 < 4; ++d0) qr[d0] = *(const bf16x8*)(qp + d0 * 16); }
;     float m = -1e30f, l = 0.f; f32x16 o[2];
;     o[0] = f32x16{}; o[1] = f32x16{};
;     const unsigned klo = (unsigned)(r32 * 1024 + hi * 8), vlo = (unsigned)(hi * 4096 + dvh * 64 + r32), kco = (unsigned)((lane >> 4) * 1024 + (lane & 15) * 4);
;     LAS float* kst = (LAS float*)(lds + 40960 + wave * 8704);
;     f32x4 kr[8]; float vr[2][16];
.LBB0_294:
	v_mbcnt_lo_u32_b32 v249, -1, 0
	v_mbcnt_hi_u32_b32 v249, -1, v249
	v_readlane_b32 s32, v251, 10
	v_lshrrev_b32_e32 v250, 1, v249
	v_and_b32_e32 v249, 1, v249
	v_lshlrev_b32_e32 v250, 12, v250
	v_lshl_or_b32 v249, v249, 7, v250
	s_bfe_u32 s32, s32, 0x10001
	s_lshl_b32 s32, s32, 8
	v_add_u32_e32 v250, s32, v249
	s_ashr_i32 s0, s90, 4
	s_lshl_b32 s4, s0, 6
	v_mbcnt_lo_u32_b32 v16, -1, 0
	v_mbcnt_hi_u32_b32 v16, -1, v16
	s_add_i32 s6, s4, 0x8000
	v_add_u32_e32 v0, s11, v16
	s_or_b32 s78, s6, s85
	v_and_b32_e32 v159, 31, v16
	v_or_b32_e32 v0, s78, v159
	s_lshl_b32 s30, s0, 11
	v_ashrrev_i32_e32 v1, 31, v0
	v_readlane_b32 s48, v251, 36
	s_add_i32 s0, s30, s95
	s_bfe_u32 s14, s90, 0x30001
	v_lshlrev_b64 v[0:1], 11, v[0:1]
	v_readlane_b32 s49, v251, 37
	s_ashr_i32 s1, s0, 31
	s_and_b32 s15, s90, 1
	v_lshl_add_u64 v[0:1], s[48:49], 0, v[0:1]
	s_lshl_b32 s20, s14, 8
	s_lshl_b64 s[0:1], s[0:1], 12
	s_lshl_b32 s79, s14, 9
	s_lshl_b32 s5, s14, 7
	v_lshl_add_u64 v[0:1], v[0:1], 0, s[20:21]
	s_lshl_b32 s7, s15, 6
	s_lshl_b32 s20, s15, 7
	s_or_b32 s0, s0, s79
	v_ashrrev_i32_e32 v17, 5, v16
	s_mul_i32 s34, s14, 0x310
	v_lshlrev_b32_e32 v160, 2, v16
	s_add_u32 s14, s40, s0
	v_lshl_add_u64 v[0:1], v[0:1], 0, s[20:21]
	v_lshlrev_b32_e32 v114, 3, v17
	v_ashrrev_i32_e32 v18, 4, v16
	v_and_b32_e32 v19, 60, v160
	s_addc_u32 s35, s41, s1
	s_lshl_b32 s20, s15, 8
	v_ashrrev_i32_e32 v115, 31, v114
	v_lshl_or_b32 v112, v18, 10, v19
	s_add_u32 s92, s14, s20
	v_lshl_add_u64 v[0:1], v[114:115], 1, v[0:1]
	s_addc_u32 s93, s35, 0
	v_add_u32_e32 v120, 0x1000, v112
	v_mov_b32_e32 v121, v113
	global_load_dwordx4 v[60:63], v[0:1], off
	global_load_dwordx4 v[56:59], v[0:1], off offset:32
	global_load_dwordx4 v[52:55], v[0:1], off offset:64
	global_load_dwordx4 v[48:51], v[0:1], off offset:96
	v_lshl_add_u64 v[0:1], v[112:113], 2, s[92:93]
	v_lshl_add_u64 v[2:3], v[120:121], 2, s[92:93]
	v_add_u32_e32 v122, 0x2000, v112
	v_mov_b32_e32 v123, v113
	v_add_u32_e32 v124, 0x3000, v112
	v_mov_b32_e32 v125, v113
	global_load_dwordx4 v[64:67], v[0:1], off
	global_load_dwordx4 v[68:71], v[2:3], off
	v_lshl_add_u64 v[0:1], v[122:123], 2, s[92:93]
	v_lshl_add_u64 v[2:3], v[124:125], 2, s[92:93]
	v_add_u32_e32 v126, 0x4000, v112
	v_mov_b32_e32 v127, v113
	v_add_u32_e32 v128, 0x5000, v112
	v_mov_b32_e32 v129, v113
	global_load_dwordx4 v[72:75], v[0:1], off
	global_load_dwordx4 v[76:79], v[2:3], off
	v_lshl_add_u64 v[0:1], v[126:127], 2, s[92:93]
	v_lshl_add_u64 v[2:3], v[128:129], 2, s[92:93]
	v_add_u32_e32 v130, 0x6000, v112
	v_mov_b32_e32 v131, v113
	v_add_u32_e32 v132, 0x7000, v112
	v_mov_b32_e32 v133, v113
	global_load_dwordx4 v[80:83], v[0:1], off
	global_load_dwordx4 v[84:87], v[2:3], off
	v_lshl_add_u64 v[0:1], v[130:131], 2, s[92:93]
	v_lshl_add_u64 v[2:3], v[132:133], 2, s[92:93]
	s_add_i32 s92, s34, 0
	s_add_i32 s92, s92, 0x1f000
	v_lshlrev_b32_e32 v4, 12, v17
	s_add_u32 s0, s42, s0
	v_or3_b32 v116, v4, s91, v159
	s_addc_u32 s1, s43, s1
	v_mov_b32_e32 v117, v113
	s_add_u32 vcc_lo, s0, 0x10000
	v_or_b32_e32 v118, 32, v116
	v_mov_b32_e32 v119, v113
	s_addc_u32 vcc_hi, s1, 0
	v_lshlrev_b64 v[134:135], 2, v[116:117]
	v_lshlrev_b64 v[136:137], 2, v[118:119]
	global_load_dwordx4 v[88:91], v[0:1], off
	global_load_dwordx4 v[92:95], v[2:3], off
	v_lshl_add_u64 v[2:3], vcc, 0, v[134:135]
	v_lshl_add_u64 v[4:5], vcc, 0, v[136:137]
	s_add_u32 vcc_lo, s0, 0x1000
	s_addc_u32 vcc_hi, s1, 0
	s_add_u32 s34, s0, 0x11000
	s_addc_u32 s35, s1, 0
	v_lshl_add_u64 v[8:9], s[34:35], 0, v[134:135]
	v_lshl_add_u64 v[12:13], s[34:35], 0, v[136:137]
	s_add_u32 s34, s0, 0x2000
	s_addc_u32 s35, s1, 0
	v_lshl_add_u64 v[6:7], vcc, 0, v[134:135]
	v_lshl_add_u64 v[10:11], vcc, 0, v[136:137]
	s_add_u32 vcc_lo, s0, 0x12000
	v_lshl_add_u64 v[0:1], s[0:1], 0, v[134:135]
	s_addc_u32 vcc_hi, s1, 0
	global_load_dword v201, v[0:1], off
	global_load_dword v196, v[2:3], off
	global_load_dword v181, v[4:5], off
	global_load_dword v203, v[6:7], off
	global_load_dword v197, v[8:9], off
	global_load_dword v185, v[10:11], off
	global_load_dword v182, v[12:13], off
	global_load_dword v187, v[0:1], off offset:128
	v_lshl_add_u64 v[0:1], s[34:35], 0, v[134:135]
	v_lshl_add_u64 v[4:5], s[34:35], 0, v[136:137]
	s_add_u32 s34, s0, 0x3000
	s_addc_u32 s35, s1, 0
	v_lshl_add_u64 v[2:3], vcc, 0, v[134:135]
	v_lshl_add_u64 v[6:7], vcc, 0, v[136:137]
	s_add_u32 vcc_lo, s0, 0x13000
	s_addc_u32 vcc_hi, s1, 0
	v_lshl_add_u64 v[8:9], s[34:35], 0, v[134:135]
	v_lshl_add_u64 v[12:13], s[34:35], 0, v[136:137]
	s_add_u32 s34, s0, 0x8000
	s_addc_u32 s35, s1, 0
	v_lshl_add_u64 v[10:11], vcc, 0, v[134:135]
	v_lshl_add_u64 v[14:15], vcc, 0, v[136:137]
	s_add_u32 vcc_lo, s0, 0x18000
	s_addc_u32 vcc_hi, s1, 0
	global_load_dword v212, v[0:1], off
	global_load_dword v208, v[2:3], off
	global_load_dword v205, v[4:5], off
	global_load_dword v198, v[6:7], off
	global_load_dword v213, v[8:9], off
	global_load_dword v209, v[10:11], off
	global_load_dword v206, v[12:13], off
	global_load_dword v199, v[14:15], off
	v_lshl_add_u64 v[0:1], s[34:35], 0, v[134:135]
	v_lshl_add_u64 v[4:5], s[34:35], 0, v[136:137]
	s_add_u32 s34, s0, 0x9000
	s_addc_u32 s35, s1, 0
	v_lshl_add_u64 v[2:3], vcc, 0, v[134:135]
	v_lshl_add_u64 v[6:7], vcc, 0, v[136:137]
	s_add_u32 vcc_lo, s0, 0x19000
	s_addc_u32 vcc_hi, s1, 0
	v_lshl_add_u64 v[8:9], s[34:35], 0, v[134:135]
	v_lshl_add_u64 v[12:13], s[34:35], 0, v[136:137]
	s_add_u32 s34, s0, 0xa000
	s_addc_u32 s35, s1, 0
	v_lshl_add_u64 v[10:11], vcc, 0, v[134:135]
	v_lshl_add_u64 v[14:15], vcc, 0, v[136:137]
	s_add_u32 vcc_lo, s0, 0x1a000
	s_addc_u32 vcc_hi, s1, 0
	global_load_dword v225, v[0:1], off
	global_load_dword v220, v[2:3], off
; #define LAS __attribute__((address_space(3)))
; __device__ __forceinline__ void sattn_unit(const Args& a, LAS unsigned char* lds, const LAS float* bt, int db, int h, int t, int tid, int wave, int lane) {
;     ...
;     float m = -1e30f, l = 0.f; f32x16 o[2];
;     o[0] = f32x16{}; o[1] = f32x16{};
;     const unsigned klo = (unsigned)(r32 * 1024 + hi * 8), vlo = (unsigned)(hi * 4096 + dvh * 64 + r32), kco = (unsigned)((lane >> 4) * 1024 + (lane & 15) * 4);
;     LAS float* kst = (LAS float*)(lds + 40960 + wave * 8704);
;     f32x4 kr[8]; float vr[2][16];
;     ...
;     const int tile0 = ksp * 33, nf = ksp ? 31 : 33;
;     SA_LOAD(tile0 * 32);
	global_load_dword v215, v[4:5], off
	global_load_dword v210, v[6:7], off
	global_load_dword v227, v[8:9], off
	global_load_dword v221, v[10:11], off
	global_load_dword v217, v[12:13], off
	global_load_dword v211, v[14:15], off
	v_lshl_add_u64 v[0:1], s[34:35], 0, v[134:135]
	v_lshl_add_u64 v[4:5], s[34:35], 0, v[136:137]
	s_add_u32 s34, s0, 0xb000
	s_addc_u32 s35, s1, 0
	s_add_u32 s0, s0, 0x1b000
	s_addc_u32 s1, s1, 0
	v_lshl_add_u64 v[2:3], vcc, 0, v[134:135]
	v_lshl_add_u64 v[6:7], vcc, 0, v[136:137]
	v_lshl_add_u64 v[8:9], s[34:35], 0, v[134:135]
	v_lshl_add_u64 v[10:11], s[0:1], 0, v[134:135]
	v_lshl_add_u64 v[12:13], s[34:35], 0, v[136:137]
	v_lshl_add_u64 v[14:15], s[0:1], 0, v[136:137]
	global_load_dword v234, v[0:1], off
	global_load_dword v232, v[2:3], off
	global_load_dword v229, v[4:5], off
	global_load_dword v222, v[6:7], off
	global_load_dword v235, v[8:9], off
	global_load_dword v233, v[10:11], off
	global_load_dword v230, v[12:13], off
	global_load_dword v223, v[14:15], off
	v_mul_u32_u24_e32 v0, 0x110, v159
	v_and_b32_e32 v1, 0xffffffe0, v16
	v_add3_u32 v170, s94, v0, v1
	v_or_b32_e32 v0, s85, v159
	v_lshlrev_b32_e32 v163, 2, v17
	v_sub_u32_e32 v168, v163, v0
	v_and_or_b32 v0, v163, 60, v191
	v_add_u32_e32 v161, 8, v163
	v_lshlrev_b32_e32 v164, 2, v0
	v_and_or_b32 v0, v161, 60, v191
	v_add_u32_e32 v157, 9, v163
	v_lshlrev_b32_e32 v162, 2, v0
	v_and_or_b32 v0, v157, 61, v191
	v_add_u32_e32 v155, 10, v163
	v_lshlrev_b32_e32 v158, 2, v0
	v_and_or_b32 v0, v155, 62, v191
	v_add_u32_e32 v153, 11, v163
	v_lshlrev_b32_e32 v156, 2, v0
	v_and_or_b32 v0, v153, 63, v191
	v_add_u32_e32 v151, 16, v163
	v_lshlrev_b32_e32 v154, 2, v0
	v_and_or_b32 v0, v151, 60, v191
	v_add_u32_e32 v149, 17, v163
	v_lshlrev_b32_e32 v152, 2, v0
	v_and_or_b32 v0, v149, 61, v191
	v_add_u32_e32 v147, 18, v163
	v_lshlrev_b32_e32 v150, 2, v0
	v_and_or_b32 v0, v147, 62, v191
	v_add_u32_e32 v145, 19, v163
	v_lshlrev_b32_e32 v148, 2, v0
	v_and_or_b32 v0, v145, 63, v191
	v_add_u32_e32 v143, 24, v163
	v_lshlrev_b32_e32 v146, 2, v0
	v_and_or_b32 v0, v143, 60, v191
	v_add_u32_e32 v141, 25, v163
	v_lshlrev_b32_e32 v144, 2, v0
	v_and_or_b32 v0, v141, 61, v191
	v_add_u32_e32 v139, 26, v163
	v_cmp_lt_i32_e32 vcc, v190, v192
	s_movk_i32 s0, 0x110
	v_lshlrev_b32_e32 v142, 2, v0
	v_and_or_b32 v0, v139, 62, v191
	v_add_u32_e32 v115, 27, v163
	s_waitcnt vmcnt(45)
	v_lshl_add_u32 v32, v19, 2, s94
	s_add_u32 s93, s40, s20
	v_cndmask_b32_e32 v1, v189, v190, vcc
	v_mul_lo_u32 v33, v18, s0
	v_lshlrev_b32_e32 v140, 2, v0
	v_and_or_b32 v0, v115, 63, v191
	s_addc_u32 s89, s41, 0
	s_mov_b32 s35, 0
	v_lshlrev_b32_e32 v194, 2, v1
	s_or_b32 s30, s30, 32
	v_add_u32_e32 v171, 0xfffff880, v168
	v_or_b32_e32 v165, 4, v164
	v_or_b32_e32 v166, 8, v164
	v_or_b32_e32 v167, 12, v164
	v_lshlrev_b32_e32 v138, 2, v0
	v_mov_b32_e32 v0, v113
	v_mov_b32_e32 v1, v113
	v_mov_b32_e32 v2, v113
	v_mov_b32_e32 v3, v113
	v_mov_b32_e32 v4, v113
	v_mov_b32_e32 v5, v113
	v_mov_b32_e32 v6, v113
	v_mov_b32_e32 v7, v113
	v_mov_b32_e32 v8, v113
	v_mov_b32_e32 v9, v113
	v_mov_b32_e32 v10, v113
	v_mov_b32_e32 v11, v113
	v_mov_b32_e32 v12, v113
	v_mov_b32_e32 v13, v113
	v_mov_b32_e32 v14, v113
	v_mov_b32_e32 v15, v113
	v_mov_b32_e32 v16, v113
	v_mov_b32_e32 v17, v113
	v_mov_b32_e32 v18, v113
	v_mov_b32_e32 v19, v113
	v_mov_b32_e32 v20, v113
	v_mov_b32_e32 v21, v113
	v_mov_b32_e32 v22, v113
	v_mov_b32_e32 v23, v113
	v_mov_b32_e32 v24, v113
	v_mov_b32_e32 v25, v113
	v_mov_b32_e32 v26, v113
	v_mov_b32_e32 v27, v113
	v_mov_b32_e32 v28, v113
	v_mov_b32_e32 v29, v113
	v_mov_b32_e32 v30, v113
	v_mov_b32_e32 v31, v113
	v_mov_b32_e32 v169, 0
	v_mov_b32_e32 v244, 0xf149f2ca
	v_add_u32_e32 v172, v32, v33
	s_waitcnt vmcnt(0)
	v_mov_b32_e32 v243, v223
	v_mov_b32_e32 v236, v222
	v_mov_b32_e32 v231, v211
	v_mov_b32_e32 v214, v210
	v_mov_b32_e32 v207, v199
	v_mov_b32_e32 v183, v198
	v_mov_b32_e32 v180, v182
	v_mov_b32_e32 v173, v181
	v_mov_b32_e32 v240, v230
	v_mov_b32_e32 v237, v229
	v_mov_b32_e32 v224, v217
	v_mov_b32_e32 v216, v215
	v_mov_b32_e32 v200, v206
	v_mov_b32_e32 v184, v205
	v_mov_b32_e32 v177, v185
	v_mov_b32_e32 v174, v187
	v_mov_b32_e32 v241, v233
	v_mov_b32_e32 v238, v232
	v_mov_b32_e32 v226, v221
	v_mov_b32_e32 v218, v220
	v_mov_b32_e32 v202, v209
	v_mov_b32_e32 v186, v208
	v_mov_b32_e32 v178, v197
	v_mov_b32_e32 v175, v196
	v_mov_b32_e32 v242, v235
	v_mov_b32_e32 v239, v234
	v_mov_b32_e32 v228, v227
	v_mov_b32_e32 v219, v225
	v_mov_b32_e32 v204, v213
	v_mov_b32_e32 v195, v212
	v_mov_b32_e32 v179, v203
	v_mov_b32_e32 v176, v201
; __device__ __forceinline__ void sattn_unit(const Args& a, LAS unsigned char* lds, const LAS float* bt, int db, int h, int t, int tid, int wave, int lane) {
;     ...
;     const int tile0 = ksp * 33, nf = ksp ? 31 : 33;
;     SA_LOAD(tile0 * 32);
;     for (int it = 0; it < nf; ++it) {
;         const int key0 = __builtin_amdgcn_readfirstlane((tile0 + it) * 32);
;         bf16x8 kf[4]; bf16x8 vf[2][2];
;         SA_CVT();
;         if (it + 1 < nf) SA_LOAD(key0 + 32);
.LBB0_295:
	ds_write_b128 v172, v[64:67] offset:40960
	ds_write_b128 v172, v[68:71] offset:42048
	ds_write_b128 v172, v[72:75] offset:43136
	ds_write_b128 v172, v[76:79] offset:44224
	ds_write_b128 v172, v[80:83] offset:45312
	ds_write_b128 v172, v[84:87] offset:46400
	ds_write_b128 v172, v[88:91] offset:47488
	ds_write_b128 v172, v[92:95] offset:48576
	ds_read_b128 v[108:111], v170 offset:40960
	ds_read_b128 v[104:107], v170 offset:40976
	ds_read_b128 v[100:103], v170 offset:41024
	ds_read_b128 v[96:99], v170 offset:41040
	ds_read_b128 v[44:47], v170 offset:41088
	ds_read_b128 v[40:43], v170 offset:41104
	ds_read_b128 v[36:39], v170 offset:41152
	ds_read_b128 v[32:35], v170 offset:41168
	s_add_i32 s0, s96, s35
	s_lshl_b32 vcc_lo, s0, 5
	s_add_i32 s35, s35, 1
	s_cmp_ge_u32 s35, s97
	s_cbranch_scc1 .LBB0_297
	s_add_i32 s0, s30, vcc_lo
	s_ashr_i32 s1, s0, 31
	s_lshl_b64 s[0:1], s[0:1], 12
	s_lshl_b32 s14, s5, 2
	s_or_b32 s0, s0, s14
	s_add_u32 s48, s93, s0
	s_addc_u32 s49, s89, s1
	s_mov_b32 s32, s48
	s_mov_b32 s34, s49
	s_add_u32 s0, s42, s0
	s_addc_u32 s1, s43, s1
	v_lshl_add_u64 v[64:65], v[112:113], 2, s[48:49]
	v_lshl_add_u64 v[68:69], v[120:121], 2, s[48:49]
	v_lshl_add_u64 v[72:73], v[122:123], 2, s[48:49]
	v_lshl_add_u64 v[76:77], v[124:125], 2, s[48:49]
	v_lshl_add_u64 v[80:81], v[126:127], 2, s[48:49]
	v_lshl_add_u64 v[84:85], v[128:129], 2, s[48:49]
	v_lshl_add_u64 v[88:89], v[130:131], 2, s[48:49]
	v_lshl_add_u64 v[92:93], v[132:133], 2, s[48:49]
	s_add_u32 s48, s0, 0x10000
	s_addc_u32 s49, s1, 0
	v_lshl_add_u64 v[178:179], s[0:1], 0, v[134:135]
	v_lshl_add_u64 v[174:175], s[48:49], 0, v[134:135]
	global_load_dwordx4 v[64:67], v[64:65], off
	s_nop 0
	global_load_dwordx4 v[68:71], v[68:69], off
	s_nop 0
	global_load_dwordx4 v[72:75], v[72:73], off
	s_nop 0
	global_load_dwordx4 v[76:79], v[76:77], off
	s_nop 0
	global_load_dwordx4 v[80:83], v[80:81], off
	s_nop 0
	global_load_dwordx4 v[84:87], v[84:85], off
	s_nop 0
	global_load_dwordx4 v[88:91], v[88:89], off
	s_nop 0
	global_load_dwordx4 v[92:95], v[92:93], off
	s_nop 0
	global_load_dword v176, v[178:179], off
	s_nop 0
	global_load_dword v175, v[174:175], off
	s_nop 0
	global_load_dword v174, v[178:179], off offset:128
	v_lshl_add_u64 v[178:179], s[48:49], 0, v[136:137]
	s_add_u32 s48, s0, 0x1000
	s_addc_u32 s49, s1, 0
	s_add_u32 s14, s0, 0x11000
	s_addc_u32 s15, s1, 0
	global_load_dword v173, v[178:179], off
	v_lshl_add_u64 v[178:179], s[48:49], 0, v[134:135]
	v_lshl_add_u64 v[218:219], s[14:15], 0, v[134:135]
	global_load_dword v179, v[178:179], off
	s_nop 0
	global_load_dword v178, v[218:219], off
	v_lshl_add_u64 v[218:219], s[48:49], 0, v[136:137]
	global_load_dword v177, v[218:219], off
	v_lshl_add_u64 v[218:219], s[14:15], 0, v[136:137]
	s_add_u32 s14, s0, 0x2000
	s_addc_u32 s15, s1, 0
	s_add_u32 s48, s0, 0x12000
	global_load_dword v180, v[218:219], off
	s_addc_u32 s49, s1, 0
	v_lshl_add_u64 v[218:219], s[14:15], 0, v[134:135]
	global_load_dword v195, v[218:219], off
	v_lshl_add_u64 v[218:219], s[48:49], 0, v[134:135]
	global_load_dword v186, v[218:219], off
	v_lshl_add_u64 v[218:219], s[14:15], 0, v[136:137]
	s_add_u32 s14, s0, 0x3000
	s_addc_u32 s15, s1, 0
	global_load_dword v184, v[218:219], off
	v_lshl_add_u64 v[218:219], s[48:49], 0, v[136:137]
	s_add_u32 s48, s0, 0x13000
	global_load_dword v183, v[218:219], off
	s_addc_u32 s49, s1, 0
	v_lshl_add_u64 v[218:219], s[14:15], 0, v[134:135]
	global_load_dword v204, v[218:219], off
	v_lshl_add_u64 v[218:219], s[48:49], 0, v[134:135]
	global_load_dword v202, v[218:219], off
	v_lshl_add_u64 v[218:219], s[14:15], 0, v[136:137]
	s_add_u32 s14, s0, 0x8000
	s_addc_u32 s15, s1, 0
	global_load_dword v200, v[218:219], off
	v_lshl_add_u64 v[218:219], s[48:49], 0, v[136:137]
	s_add_u32 s48, s0, 0x18000
	s_addc_u32 s49, s1, 0
	global_load_dword v207, v[218:219], off
	v_lshl_add_u64 v[218:219], s[14:15], 0, v[134:135]
	v_lshl_add_u64 v[236:237], s[48:49], 0, v[134:135]
	global_load_dword v219, v[218:219], off
	s_nop 0
	global_load_dword v218, v[236:237], off
	v_lshl_add_u64 v[236:237], s[14:15], 0, v[136:137]
	s_add_u32 s14, s0, 0x9000
	s_addc_u32 s15, s1, 0
	global_load_dword v216, v[236:237], off
	v_lshl_add_u64 v[236:237], s[48:49], 0, v[136:137]
	s_add_u32 s48, s0, 0x19000
	global_load_dword v214, v[236:237], off
	s_addc_u32 s49, s1, 0
	v_lshl_add_u64 v[236:237], s[14:15], 0, v[134:135]
	global_load_dword v228, v[236:237], off
	v_lshl_add_u64 v[236:237], s[48:49], 0, v[134:135]
	global_load_dword v226, v[236:237], off
	v_lshl_add_u64 v[236:237], s[14:15], 0, v[136:137]
	s_add_u32 s14, s0, 0xa000
	s_addc_u32 s15, s1, 0
	global_load_dword v224, v[236:237], off
	v_lshl_add_u64 v[236:237], s[48:49], 0, v[136:137]
	s_add_u32 s48, s0, 0x1a000
	global_load_dword v231, v[236:237], off
	s_addc_u32 s49, s1, 0
	v_lshl_add_u64 v[236:237], s[14:15], 0, v[134:135]
	global_load_dword v239, v[236:237], off
	v_lshl_add_u64 v[236:237], s[48:49], 0, v[134:135]
	global_load_dword v238, v[236:237], off
	v_lshl_add_u64 v[236:237], s[14:15], 0, v[136:137]
	s_add_u32 s14, s0, 0xb000
	s_addc_u32 s15, s1, 0
	v_lshl_add_u64 v[240:241], s[48:49], 0, v[136:137]
	s_add_u32 s0, s0, 0x1b000
	global_load_dword v237, v[236:237], off
	s_addc_u32 s1, s1, 0
	global_load_dword v236, v[240:241], off
	v_lshl_add_u64 v[240:241], s[14:15], 0, v[134:135]
	global_load_dword v242, v[240:241], off
	v_lshl_add_u64 v[240:241], s[0:1], 0, v[134:135]
	v_lshl_add_u64 v[246:247], s[14:15], 0, v[136:137]
	global_load_dword v241, v[240:241], off
	s_nop 0
	global_load_dword v240, v[246:247], off
	v_lshl_add_u64 v[246:247], s[0:1], 0, v[136:137]
	global_load_dword v243, v[246:247], off
	s_add_i32 s81, s35, 2
	s_cmp_lt_u32 s81, s97
	s_cselect_b32 s81, 0x40000, 0
	s_add_u32 s48, s32, s81
	s_addc_u32 s49, s34, 0
	s_sub_u32 s14, s0, 0x1b000
	s_subb_u32 s15, s1, 0
	s_add_u32 s14, s14, s81
	s_addc_u32 s15, s15, 0
	global_load_dword v248, v249, s[48:49]
	global_load_dword v248, v250, s[14:15]

; __device__ __forceinline__ int crow(int r,int hi){return (r&3)+8*(r>>2)+4*hi;}
; __device__ __forceinline__ int crow(int r, int hi) { return (r & 3) + 8 * (r >> 2) + 4 * hi; }
; __device__ __forceinline__ void sattn_unit(const Args& a, LAS unsigned char* lds, const LAS float* bt, int db, int h, int t, int tid, int wave, int lane) {
;     ...
;     const int tile0 = ksp * 33, nf = ksp ? 31 : 33;
;     SA_LOAD(tile0 * 32);
;     for (int it = 0; it < nf; ++it) {
;         const int key0 = __builtin_amdgcn_readfirstlane((tile0 + it) * 32);
;         bf16x8 kf[4]; bf16x8 vf[2][2];
;         SA_CVT();
;         if (it + 1 < nf) SA_LOAD(key0 + 32);
;         SA_COMPUTE(key0);
;     }
;     if (ksp == 1) {
;         for (int it = 0; it < 2; ++it) {
;             const int key0 = 2048 + it * 32;
;             bf16x8 kf[4]; bf16x8 vf[2][2];
;             const bf16* kpu = Kb + (size_t)(MP + db * 64 + key0 - 2048) * 1024 + h * 128 + t * 64;
;             const bf16* vpu = Vb + (size_t)(MP + db * 64 + key0 - 2048) * 1024 + h * 128;
; #pragma unroll
;             for (int d0 = 0; d0 < 4; ++d0) kf[d0] = *(const bf16x8*)(kpu + (klo + d0 * 16));
; #pragma unroll
;             for (int e = 0; e < 8; ++e) { const bf16* r0 = vpu + crow(e, 0) * 1024; const bf16* r1 = vpu + (16 + crow(e, 0)) * 1024;
; #pragma unroll
;                 for (int d2 = 0; d2 < 2; ++d2) { vf[d2][0][e] = (short)r0[vlo + d2 * 32]; vf[d2][1][e] = (short)r1[vlo + d2 * 32]; } }
.LBB0_301:
	v_sub_f32_e32 v32, v32, v104
	v_exp_f32_e32 v32, v32
	v_sub_f32_e32 v33, v33, v104
	v_exp_f32_e32 v33, v33
	v_sub_f32_e32 v34, v34, v104
	v_exp_f32_e32 v34, v34
	v_sub_f32_e32 v35, v35, v104
	v_sub_f32_e32 v36, v36, v104
	v_sub_f32_e32 v37, v37, v104
	v_sub_f32_e32 v38, v38, v104
	v_sub_f32_e32 v39, v39, v104
	v_exp_f32_e32 v35, v35
	v_exp_f32_e32 v36, v36
	v_exp_f32_e32 v37, v37
	v_exp_f32_e32 v38, v38
	v_exp_f32_e32 v39, v39
	v_add_f32_e32 v105, 0, v32
	v_add_f32_e32 v105, v33, v105
	v_add_f32_e32 v105, v34, v105
	v_add_f32_e32 v105, v35, v105
	v_cvt_pk_bf16_f32 v32, v32, v33
	v_cvt_pk_bf16_f32 v33, v34, v35
	v_cvt_pk_bf16_f32 v34, v36, v37
	v_cvt_pk_bf16_f32 v35, v38, v39
	v_sub_f32_e32 v40, v40, v104
	v_sub_f32_e32 v41, v41, v104
	v_sub_f32_e32 v42, v42, v104
	v_sub_f32_e32 v43, v43, v104
	v_sub_f32_e32 v44, v44, v104
	v_sub_f32_e32 v45, v45, v104
	v_sub_f32_e32 v46, v46, v104
	v_sub_f32_e32 v47, v47, v104
	v_cvt_pk_bf16_f32 v106, v201, v203
	v_cvt_pk_bf16_f32 v107, v212, v213
	v_cvt_pk_bf16_f32 v108, v225, v227
	v_cvt_pk_bf16_f32 v109, v234, v235
	v_cvt_pk_bf16_f32 v100, v187, v185
	v_cvt_pk_bf16_f32 v101, v205, v206
	v_cvt_pk_bf16_f32 v102, v215, v217
	v_cvt_pk_bf16_f32 v103, v229, v230
	v_exp_f32_e32 v40, v40
	v_exp_f32_e32 v41, v41
	v_exp_f32_e32 v42, v42
	v_exp_f32_e32 v43, v43
	v_exp_f32_e32 v44, v44
	v_exp_f32_e32 v45, v45
	v_exp_f32_e32 v46, v46
	v_exp_f32_e32 v47, v47
	v_add_f32_e32 v105, v36, v105
	v_mfma_f32_32x32x16_bf16 v[0:15], v[32:35], v[106:109], v[0:15]
	v_add_f32_e32 v105, v37, v105
	v_add_f32_e32 v105, v38, v105
	v_add_f32_e32 v105, v39, v105
	v_cvt_pk_bf16_f32 v36, v40, v41
	v_cvt_pk_bf16_f32 v37, v42, v43
	v_cvt_pk_bf16_f32 v38, v44, v45
	v_cvt_pk_bf16_f32 v39, v46, v47
	v_mfma_f32_32x32x16_bf16 v[16:31], v[32:35], v[100:103], v[16:31]
	v_cvt_pk_bf16_f32 v244, v196, v197
	v_cvt_pk_bf16_f32 v245, v208, v209
	v_cvt_pk_bf16_f32 v246, v220, v221
	v_cvt_pk_bf16_f32 v247, v232, v233
	v_cvt_pk_bf16_f32 v96, v181, v182
	v_cvt_pk_bf16_f32 v97, v198, v199
	v_cvt_pk_bf16_f32 v98, v210, v211
	v_cvt_pk_bf16_f32 v99, v222, v223
	v_add_f32_e32 v105, v40, v105
	v_add_f32_e32 v105, v41, v105
	v_mfma_f32_32x32x16_bf16 v[0:15], v[36:39], v[244:247], v[0:15]
	v_add_f32_e32 v105, v42, v105
	v_add_f32_e32 v105, v43, v105
	v_add_f32_e32 v105, v44, v105
	v_add_f32_e32 v105, v45, v105
	v_add_f32_e32 v105, v46, v105
	v_add_f32_e32 v105, v47, v105
	v_add_f32_e32 v169, v105, v169
	v_mfma_f32_32x32x16_bf16 v[16:31], v[36:39], v[96:99], v[16:31]
	s_cmp_eq_u32 s97, s35
	s_cbranch_scc1 .LBB0_303
	s_waitcnt vmcnt(2)
	v_mov_b32_e32 v223, v243
	v_mov_b32_e32 v222, v236
	v_mov_b32_e32 v211, v231
	v_mov_b32_e32 v210, v214
	v_mov_b32_e32 v199, v207
	v_mov_b32_e32 v198, v183
	v_mov_b32_e32 v182, v180
	v_mov_b32_e32 v181, v173
	v_mov_b32_e32 v230, v240
	v_mov_b32_e32 v229, v237
	v_mov_b32_e32 v217, v224
	v_mov_b32_e32 v215, v216
	v_mov_b32_e32 v206, v200
	v_mov_b32_e32 v205, v184
	v_mov_b32_e32 v185, v177
	v_mov_b32_e32 v187, v174
	v_mov_b32_e32 v233, v241
	v_mov_b32_e32 v232, v238
	v_mov_b32_e32 v221, v226
	v_mov_b32_e32 v220, v218
	v_mov_b32_e32 v209, v202
	v_mov_b32_e32 v208, v186
	v_mov_b32_e32 v197, v178
	v_mov_b32_e32 v196, v175
	v_mov_b32_e32 v235, v242
	v_mov_b32_e32 v234, v239
	v_mov_b32_e32 v227, v228
	v_mov_b32_e32 v225, v219
	v_mov_b32_e32 v213, v204
	v_mov_b32_e32 v212, v195
	v_mov_b32_e32 v203, v179
	v_mov_b32_e32 v201, v176
	v_mov_b32_e32 v244, v104
	s_branch .LBB0_295
.LBB0_303:
	s_waitcnt vmcnt(0)
	v_cndmask_b32_e64 v32, 0, 1, s[26:27]
	v_cmp_ne_u32_e64 s[0:1], 1, v32
	s_andn2_b64 vcc, exec, s[26:27]
	s_cbranch_vccnz .LBB0_309
	s_lshl_b32 s5, s5, 1
	v_readlane_b32 s14, v251, 26
	s_add_u32 s14, s14, s5
	v_readlane_b32 s15, v251, 28
	s_addc_u32 s15, s15, 0
	s_lshl_b32 s7, s7, 1
	s_add_u32 s89, s14, s7
	s_addc_u32 s93, s15, 0
	s_add_u32 s30, s82, s5
	v_readlane_b32 s5, v251, 32
	s_addc_u32 s35, s5, 0
	s_ashr_i32 s7, s6, 31
	s_lshl_b64 s[6:7], s[6:7], 11
	s_add_u32 vcc_lo, s89, s6
	v_lshl_add_u32 v112, v159, 10, v114
	s_addc_u32 vcc_hi, s93, s7
	v_lshl_add_u64 v[32:33], v[112:113], 1, vcc
	global_load_dwordx4 v[32:35], v[32:33], off
	s_waitcnt vmcnt(35)
	v_add_u32_e32 v84, 16, v112
	v_mov_b32_e32 v85, v113
	v_lshl_add_u64 v[36:37], v[84:85], 1, vcc
	global_load_dwordx4 v[72:75], v[36:37], off
	v_add_u32_e32 v80, 32, v112
	v_mov_b32_e32 v81, v113
	v_lshl_add_u64 v[36:37], v[80:81], 1, vcc
	global_load_dwordx4 v[68:71], v[36:37], off
	v_add_u32_e32 v82, 48, v112
	v_mov_b32_e32 v83, v113
	v_lshl_add_u64 v[36:37], v[82:83], 1, vcc
	global_load_dwordx4 v[64:67], v[36:37], off
	s_add_u32 s6, s30, s6
	s_addc_u32 s7, s35, s7
	s_add_u32 vcc_lo, s6, 0x8000
	s_addc_u32 vcc_hi, s7, 0
	v_lshlrev_b64 v[76:77], 1, v[116:117]
	v_lshl_add_u64 v[36:37], s[6:7], 0, v[76:77]
	v_lshl_add_u64 v[38:39], vcc, 0, v[76:77]
	v_lshlrev_b64 v[78:79], 1, v[118:119]
	global_load_ushort v91, v[36:37], off
	global_load_ushort v89, v[38:39], off
	global_load_ushort v87, v[36:37], off offset:64
	v_lshl_add_u64 v[38:39], vcc, 0, v[78:79]
	s_add_u32 vcc_lo, s6, 0x8800
	s_addc_u32 vcc_hi, s7, 0
	global_load_ushort v88, v[38:39], off
	global_load_ushort v94, v[36:37], off offset:2048
	v_lshl_add_u64 v[38:39], vcc, 0, v[76:77]
	global_load_ushort v92, v[38:39], off
	global_load_ushort v90, v[36:37], off offset:2112
	v_lshl_add_u64 v[36:37], vcc, 0, v[78:79]
	s_add_u32 vcc_lo, s6, 0x1000
	s_addc_u32 vcc_hi, s7, 0
	s_add_u32 s48, s6, 0x9000
	global_load_ushort v93, v[36:37], off
	s_addc_u32 s49, s7, 0
	v_lshl_add_u64 v[36:37], vcc, 0, v[76:77]
	global_load_ushort v98, v[36:37], off
	v_lshl_add_u64 v[36:37], s[48:49], 0, v[76:77]
	global_load_ushort v97, v[36:37], off
; __device__ __forceinline__ int crow(int r,int hi){return (r&3)+8*(r>>2)+4*hi;}
; __device__ __forceinline__ int crow(int r, int hi) { return (r & 3) + 8 * (r >> 2) + 4 * hi; }
; __device__ __forceinline__ void sattn_unit(const Args& a, LAS unsigned char* lds, const LAS float* bt, int db, int h, int t, int tid, int wave, int lane) {
;     ...
;             const bf16* kpu = Kb + (size_t)(MP + db * 64 + key0 - 2048) * 1024 + h * 128 + t * 64;
;             const bf16* vpu = Vb + (size_t)(MP + db * 64 + key0 - 2048) * 1024 + h * 128;
; #pragma unroll
;             for (int d0 = 0; d0 < 4; ++d0) kf[d0] = *(const bf16x8*)(kpu + (klo + d0 * 16));
; #pragma unroll
;             for (int e = 0; e < 8; ++e) { const bf16* r0 = vpu + crow(e, 0) * 1024; const bf16* r1 = vpu + (16 + crow(e, 0)) * 1024;
; #pragma unroll
;                 for (int d2 = 0; d2 < 2; ++d2) { vf[d2][0][e] = (short)r0[vlo + d2 * 32]; vf[d2][1][e] = (short)r1[vlo + d2 * 32]; } }
;             SA_COMPUTE(key0);
	v_lshl_add_u64 v[36:37], vcc, 0, v[78:79]
	global_load_ushort v95, v[36:37], off
	v_lshl_add_u64 v[36:37], s[48:49], 0, v[78:79]
	s_add_u32 s48, s6, 0x1800
	s_addc_u32 s49, s7, 0
	s_add_u32 vcc_lo, s6, 0x9800
	global_load_ushort v96, v[36:37], off
	s_addc_u32 vcc_hi, s7, 0
	v_lshl_add_u64 v[36:37], s[48:49], 0, v[76:77]
	global_load_ushort v102, v[36:37], off
	v_lshl_add_u64 v[36:37], vcc, 0, v[76:77]
	global_load_ushort v100, v[36:37], off
	v_lshl_add_u64 v[36:37], s[48:49], 0, v[78:79]
	s_add_u32 s48, s6, 0x4000
	s_addc_u32 s49, s7, 0
	global_load_ushort v99, v[36:37], off
	v_lshl_add_u64 v[36:37], vcc, 0, v[78:79]
	s_add_u32 vcc_lo, s6, 0xc000
	global_load_ushort v101, v[36:37], off
	s_addc_u32 vcc_hi, s7, 0
	v_lshl_add_u64 v[36:37], s[48:49], 0, v[76:77]
	global_load_ushort v107, v[36:37], off
	v_lshl_add_u64 v[36:37], vcc, 0, v[76:77]
	global_load_ushort v106, v[36:37], off
	v_lshl_add_u64 v[36:37], s[48:49], 0, v[78:79]
	s_add_u32 s48, s6, 0x4800
	s_addc_u32 s49, s7, 0
	global_load_ushort v103, v[36:37], off
	v_lshl_add_u64 v[36:37], vcc, 0, v[78:79]
	s_add_u32 vcc_lo, s6, 0xc800
	global_load_ushort v105, v[36:37], off
	s_addc_u32 vcc_hi, s7, 0
	v_lshl_add_u64 v[36:37], s[48:49], 0, v[76:77]
	global_load_ushort v111, v[36:37], off
	v_lshl_add_u64 v[36:37], vcc, 0, v[76:77]
	global_load_ushort v109, v[36:37], off
	v_lshl_add_u64 v[36:37], s[48:49], 0, v[78:79]
	s_add_u32 s48, s6, 0x5000
	s_addc_u32 s49, s7, 0
	v_lshl_add_u64 v[118:119], s[48:49], 0, v[78:79]
	global_load_ushort v108, v[36:37], off
	s_nop 0
	global_load_ushort v118, v[118:119], off
	v_lshl_add_u64 v[36:37], vcc, 0, v[78:79]
	s_add_u32 vcc_lo, s6, 0xd000
	s_addc_u32 vcc_hi, s7, 0
	v_lshl_add_u64 v[120:121], vcc, 0, v[78:79]
	global_load_ushort v110, v[36:37], off
	global_load_ushort v117, v[120:121], off
	v_lshl_add_u64 v[36:37], s[48:49], 0, v[76:77]
	global_load_ushort v116, v[36:37], off
	v_lshl_add_u64 v[36:37], vcc, 0, v[76:77]
	global_load_ushort v114, v[36:37], off
	s_waitcnt vmcnt(31)
	v_mfma_f32_32x32x16_bf16 v[32:47], v[32:35], v[60:63], 0
	s_add_u32 s48, s6, 0x5800
	s_addc_u32 s49, s7, 0
	s_add_u32 s6, s6, 0xd800
	s_addc_u32 s7, s7, 0
	v_lshl_add_u64 v[120:121], s[48:49], 0, v[78:79]
	s_waitcnt vmcnt(30)
	v_mfma_f32_32x32x16_bf16 v[32:47], v[72:75], v[56:59], v[32:47]
	v_lshl_add_u64 v[72:73], s[48:49], 0, v[76:77]
	global_load_ushort v74, v[72:73], off
	s_waitcnt vmcnt(30)
	v_mfma_f32_32x32x16_bf16 v[32:47], v[68:71], v[52:55], v[32:47]
	v_lshl_add_u64 v[68:69], s[6:7], 0, v[78:79]
	global_load_ushort v68, v[68:69], off
	v_lshl_add_u64 v[72:73], s[6:7], 0, v[76:77]
	global_load_ushort v73, v[72:73], off
	v_max_i32_e32 v69, 0xffffff80, v168
	global_load_ushort v72, v[120:121], off
	v_add_u32_e32 v69, 0x80, v69
	s_waitcnt vmcnt(32)
	v_mfma_f32_32x32x16_bf16 v[32:47], v[64:67], v[48:51], v[32:47]
	v_max_i32_e32 v64, 0xffffff7f, v168
	v_max_i32_e32 v65, 0xffffff7e, v168
	v_add_u32_e32 v64, 0x81, v64
	v_add_u32_e32 v65, 0x82, v65
	v_min_u32_e32 v69, 0xc0, v69
	v_min_u32_e32 v64, 0xc0, v64
	v_min_u32_e32 v65, 0xc0, v65
	v_lshl_add_u32 v69, v69, 2, s92
	v_lshl_add_u32 v64, v64, 2, s92
	v_lshl_add_u32 v65, v65, 2, s92
	ds_read_b32 v69, v69
	ds_read_b32 v64, v64
	ds_read_b32 v66, v65
	v_max_i32_e32 v65, 0xffffff7d, v168
	v_add_u32_e32 v65, 0x83, v65
	v_min_u32_e32 v65, 0xc0, v65
	v_lshl_add_u32 v65, v65, 2, s92
	ds_read_b32 v67, v65
	v_max_i32_e32 v65, 0xffffff78, v168
	v_add_u32_e32 v65, 0x88, v65
	v_min_u32_e32 v65, 0xc0, v65
	v_lshl_add_u32 v65, v65, 2, s92
	s_waitcnt lgkmcnt(3)
	v_add_f32_e32 v32, v32, v69
	ds_read_b32 v69, v65
	v_max_i32_e32 v65, 0xffffff77, v168
	v_add_u32_e32 v65, 0x89, v65
	v_min_u32_e32 v65, 0xc0, v65
	v_lshl_add_u32 v65, v65, 2, s92
	ds_read_b32 v70, v65
	s_waitcnt lgkmcnt(4)
	v_add_f32_e32 v65, v33, v64
	s_waitcnt lgkmcnt(3)
	v_add_f32_e32 v64, v34, v66
	s_waitcnt lgkmcnt(1)
	v_add_f32_e32 v34, v36, v69
	v_max_i32_e32 v36, 0xffffff76, v168
	s_waitcnt lgkmcnt(0)
	v_add_f32_e32 v33, v37, v70
	v_max_i32_e32 v37, 0xffffff75, v168
	v_max_i32_e32 v66, 0xffffff70, v168
	v_add_u32_e32 v36, 0x8a, v36
	v_add_u32_e32 v37, 0x8b, v37
	v_add_u32_e32 v66, 0x90, v66
	v_min_u32_e32 v36, 0xc0, v36
	v_min_u32_e32 v37, 0xc0, v37
	v_min_u32_e32 v66, 0xc0, v66
	v_lshl_add_u32 v36, v36, 2, s92
	v_lshl_add_u32 v37, v37, 2, s92
	v_lshl_add_u32 v66, v66, 2, s92
	v_add_f32_e32 v35, v35, v67
	ds_read_b32 v36, v36
	ds_read_b32 v37, v37
	ds_read_b32 v67, v66
	v_max_i32_e32 v66, 0xffffff6f, v168
	v_add_u32_e32 v66, 0x91, v66
	v_min_u32_e32 v66, 0xc0, v66
	v_lshl_add_u32 v66, v66, 2, s92
	ds_read_b32 v69, v66
	v_max_i32_e32 v66, 0xffffff6e, v168
	v_add_u32_e32 v66, 0x92, v66
	v_min_u32_e32 v66, 0xc0, v66
	v_lshl_add_u32 v66, v66, 2, s92
	ds_read_b32 v70, v66
	s_waitcnt lgkmcnt(4)
	v_add_f32_e32 v66, v38, v36
	s_waitcnt lgkmcnt(3)
	v_add_f32_e32 v39, v39, v37
	s_waitcnt lgkmcnt(2)
	v_add_f32_e32 v38, v40, v67
	s_waitcnt lgkmcnt(1)
	v_add_f32_e32 v37, v41, v69
	v_max_i32_e32 v40, 0xffffff6d, v168
	v_max_i32_e32 v41, 0xffffff68, v168
	s_waitcnt lgkmcnt(0)
	v_add_f32_e32 v36, v42, v70
	v_add_u32_e32 v40, 0x93, v40
	v_add_u32_e32 v41, 0x98, v41
	v_max_i32_e32 v42, 0xffffff67, v168
	v_max_i32_e32 v67, 0xffffff66, v168
	v_min_u32_e32 v40, 0xc0, v40
	v_min_u32_e32 v41, 0xc0, v41
	v_add_u32_e32 v42, 0x99, v42
	v_add_u32_e32 v67, 0x9a, v67
	v_lshl_add_u32 v40, v40, 2, s92
	v_lshl_add_u32 v41, v41, 2, s92
	v_min_u32_e32 v42, 0xc0, v42
	v_min_u32_e32 v67, 0xc0, v67
	ds_read_b32 v40, v40
	ds_read_b32 v41, v41
	v_lshl_add_u32 v42, v42, 2, s92
	v_lshl_add_u32 v67, v67, 2, s92
	ds_read_b32 v42, v42
	ds_read_b32 v69, v67
	v_max_i32_e32 v67, 0xffffff65, v168
	v_add_u32_e32 v67, 0x9b, v67
	v_min_u32_e32 v67, 0xc0, v67
	v_lshl_add_u32 v67, v67, 2, s92
	ds_read_b32 v70, v67
	s_waitcnt lgkmcnt(4)
	v_add_f32_e32 v67, v43, v40
	s_waitcnt lgkmcnt(3)
	v_add_f32_e32 v43, v44, v41
	v_max3_f32 v44, v32, s31, v65
	v_max3_f32 v44, v44, v64, v35
	v_max3_f32 v44, v44, v34, v33
	v_max3_f32 v44, v44, v66, v39
	v_max3_f32 v44, v44, v38, v37
	s_waitcnt lgkmcnt(2)
	v_add_f32_e32 v42, v45, v42
	v_max3_f32 v44, v44, v36, v67
	s_waitcnt lgkmcnt(1)
	v_add_f32_e32 v40, v46, v69
	s_waitcnt lgkmcnt(0)
	v_add_f32_e32 v41, v47, v70
	v_max3_f32 v44, v44, v43, v42
	v_max3_f32 v44, v44, v40, v41
	ds_bpermute_b32 v45, v194, v44
	s_waitcnt lgkmcnt(0)
	v_max3_f32 v86, v104, v44, v45
	v_cmp_gt_f32_e32 vcc, v86, v104
	s_cbranch_vccz .LBB0_306
	v_sub_f32_e32 v44, v104, v86
	v_exp_f32_e32 v69, v44
	ds_bpermute_b32 v44, v164, v69
	ds_bpermute_b32 v45, v165, v69
	ds_bpermute_b32 v46, v166, v69
	ds_bpermute_b32 v47, v167, v69
	ds_bpermute_b32 v70, v162, v69
	ds_bpermute_b32 v71, v158, v69
	ds_bpermute_b32 v120, v156, v69
	ds_bpermute_b32 v122, v152, v69
	ds_bpermute_b32 v124, v148, v69
	ds_bpermute_b32 v126, v144, v69
	ds_bpermute_b32 v128, v140, v69
	ds_bpermute_b32 v129, v138, v69
	ds_bpermute_b32 v127, v142, v69
	ds_bpermute_b32 v125, v146, v69
	ds_bpermute_b32 v123, v150, v69
	ds_bpermute_b32 v121, v154, v69
	s_waitcnt lgkmcnt(4)
	v_pk_mul_f32 v[14:15], v[14:15], v[128:129]
	s_waitcnt lgkmcnt(3)
	v_pk_mul_f32 v[12:13], v[12:13], v[126:127]
	s_waitcnt lgkmcnt(2)
	v_pk_mul_f32 v[10:11], v[10:11], v[124:125]
	s_waitcnt lgkmcnt(1)
	v_pk_mul_f32 v[8:9], v[8:9], v[122:123]
	s_waitcnt lgkmcnt(0)
	v_pk_mul_f32 v[6:7], v[6:7], v[120:121]
	v_pk_mul_f32 v[4:5], v[4:5], v[70:71]
	v_pk_mul_f32 v[2:3], v[2:3], v[46:47]
	v_pk_mul_f32 v[0:1], v[0:1], v[44:45]
	v_pk_mul_f32 v[30:31], v[30:31], v[128:129]
	v_pk_mul_f32 v[28:29], v[28:29], v[126:127]
	v_pk_mul_f32 v[26:27], v[26:27], v[124:125]
	v_pk_mul_f32 v[24:25], v[24:25], v[122:123]
	v_pk_mul_f32 v[22:23], v[22:23], v[120:121]
	v_pk_mul_f32 v[20:21], v[20:21], v[70:71]
	v_pk_mul_f32 v[18:19], v[18:19], v[46:47]
	v_pk_mul_f32 v[16:17], v[16:17], v[44:45]
	v_mul_f32_e32 v169, v169, v69
